# v33 + attention tile loops: back edge rotated (s_cselect + one taken s_cbranch_scc1 instead of not-taken cbranch + s_mov + s_branch) (7.11)
# baseline (speedup 1.0000x reference)
; template <int DQ, bool NA, int NQG>
; DI void attn_wg(const half_t* Qp, const half_t* Kp, const half_t* Vp, int q0, bool active, int seg0_start, int seg0_tiles,
;                 int seg1_start, int seg1_tiles, const float* rpb_h, int rq, char* smem, int tid, f16v (&O)[2][NQG]) {
;     ...
;   for (int it = 0; it < ntiles; ++it) {
;     const int k0 = (it < seg0_tiles) ? seg0_start + it * 64 : seg1_start + (it - seg0_tiles) * 64;
;     const bool more = it + 1 < ntiles;
;     ...
;     __syncthreads();
;   }
.LBB0_1928:
	s_cmp_lg_u32 s46, s35
	s_waitcnt lgkmcnt(0)
	s_barrier
	s_cselect_b32 s22, s46, s22
	s_cbranch_scc1 .LBB0_1913

; template <int DQ, bool NA, int NQG>
; DI void attn_wg(const half_t* Qp, const half_t* Kp, const half_t* Vp, int q0, bool active, int seg0_start, int seg0_tiles,
;                 int seg1_start, int seg1_tiles, const float* rpb_h, int rq, char* smem, int tid, f16v (&O)[2][NQG]) {
;     ...
;   for (int it = 0; it < ntiles; ++it) {
;     const int k0 = (it < seg0_tiles) ? seg0_start + it * 64 : seg1_start + (it - seg0_tiles) * 64;
;     const bool more = it + 1 < ntiles;
;     ...
;     __syncthreads();
;   }
.LBB0_2050:
	s_cmp_lg_u32 s21, s35
	s_waitcnt lgkmcnt(0)
	s_barrier
	s_cselect_b32 s18, s21, s18
	s_cbranch_scc1 .LBB0_2035

; template <int DQ, bool NA, int NQG>
; DI void attn_wg(const half_t* Qp, const half_t* Kp, const half_t* Vp, int q0, bool active, int seg0_start, int seg0_tiles,
;                 int seg1_start, int seg1_tiles, const float* rpb_h, int rq, char* smem, int tid, f16v (&O)[2][NQG]) {
;     ...
;   for (int it = 0; it < ntiles; ++it) {
;     const int k0 = (it < seg0_tiles) ? seg0_start + it * 64 : seg1_start + (it - seg0_tiles) * 64;
;     const bool more = it + 1 < ntiles;
;     ...
;     __syncthreads();
;   }
.LBB0_2072:
	s_cmp_lg_u32 s18, s35
	s_waitcnt lgkmcnt(0)
	s_barrier
	s_cselect_b32 s19, s18, s19
	s_cbranch_scc1 .LBB0_2057
